# v122: final output rows stored with nt policy in the fused final-norm parts (written once, never re-read), on top of v121
# speedup vs baseline: 1.0076x; 1.0021x over previous
.Lp45_ready:
	s_barrier
	s_lshl_b32 s66, s64, 8
	s_and_b32 s67, s84, 3
	s_lshl_b32 s67, s67, 6
	s_add_i32 s66, s66, s67
	s_lshl_b32 s67, s74, 3
	s_add_i32 s66, s66, s67
	s_cmp_lt_u32 s66, 0x8000
	s_cselect_b32 s52, s12, s14
	s_cselect_b32 s53, s13, s15
	s_cselect_b32 s67, 0, 0x8000
	s_sub_u32 s67, s66, s67
	s_lshl_b32 s67, s67, 12
	s_add_u32 s52, s52, s67
	s_addc_u32 s53, s53, 0
	v_readlane_b32 s54, v254, 22
	v_readlane_b32 s55, v254, 23
	s_lshl_b32 s67, s66, 11
	s_add_u32 s54, s54, s67
	s_addc_u32 s55, s55, 0
	s_lshl_b32 s67, s66, 12
	s_add_u32 s56, s40, s67
	s_addc_u32 s57, s41, 0
	v_mov_b32_e32 v124, 0x358637bd
	global_load_dwordx4 v[196:199], v194, s[38:39] offset:0
	global_load_dwordx4 v[200:203], v194, s[38:39] offset:1024
	global_load_dwordx4 v[204:207], v194, s[38:39] offset:2048
	global_load_dwordx4 v[208:211], v194, s[38:39] offset:3072
	s_mov_b64 s[2:3], s[52:53]
	s_mov_b64 s[44:45], s[56:57]
	s_mov_b64 s[26:27], s[54:55]
	global_load_dwordx2 v[82:83], v188, s[26:27] offset:0 sc1
	global_load_dwordx2 v[84:85], v188, s[26:27] offset:512 sc1
	global_load_dwordx2 v[86:87], v188, s[26:27] offset:1024 sc1
	global_load_dwordx2 v[88:89], v188, s[26:27] offset:1536 sc1
	global_load_dwordx4 v[18:21], v194, s[2:3] offset:0 nt
	global_load_dwordx4 v[22:25], v194, s[2:3] offset:1024 nt
	global_load_dwordx4 v[26:29], v194, s[2:3] offset:2048 nt
	global_load_dwordx4 v[30:33], v194, s[2:3] offset:3072 nt
	s_add_u32 s4, s52, 0x1000
	s_addc_u32 s5, s53, 0
	s_add_u32 s46, s56, 0x1000
	s_addc_u32 s47, s57, 0
	s_add_u32 s28, s54, 0x800
	s_addc_u32 s29, s55, 0
	global_load_dwordx2 v[90:91], v188, s[28:29] offset:0 sc1
	global_load_dwordx2 v[92:93], v188, s[28:29] offset:512 sc1
	global_load_dwordx2 v[94:95], v188, s[28:29] offset:1024 sc1
	global_load_dwordx2 v[96:97], v188, s[28:29] offset:1536 sc1
	global_load_dwordx4 v[34:37], v194, s[4:5] offset:0 nt
	global_load_dwordx4 v[38:41], v194, s[4:5] offset:1024 nt
	global_load_dwordx4 v[42:45], v194, s[4:5] offset:2048 nt
	global_load_dwordx4 v[46:49], v194, s[4:5] offset:3072 nt
	s_add_u32 s6, s52, 0x2000
	s_addc_u32 s7, s53, 0
	s_add_u32 s48, s56, 0x2000
	s_addc_u32 s49, s57, 0
	s_add_u32 s30, s54, 0x1000
	s_addc_u32 s31, s55, 0
	global_load_dwordx2 v[98:99], v188, s[30:31] offset:0 sc1
	global_load_dwordx2 v[100:101], v188, s[30:31] offset:512 sc1
	global_load_dwordx2 v[102:103], v188, s[30:31] offset:1024 sc1
	global_load_dwordx2 v[104:105], v188, s[30:31] offset:1536 sc1
	global_load_dwordx4 v[50:53], v194, s[6:7] offset:0 nt
	global_load_dwordx4 v[54:57], v194, s[6:7] offset:1024 nt
	global_load_dwordx4 v[58:61], v194, s[6:7] offset:2048 nt
	global_load_dwordx4 v[62:65], v194, s[6:7] offset:3072 nt
	s_add_u32 s8, s52, 0x3000
	s_addc_u32 s9, s53, 0
	s_add_u32 s50, s56, 0x3000
	s_addc_u32 s51, s57, 0
	s_add_u32 s34, s54, 0x1800
	s_addc_u32 s35, s55, 0
	global_load_dwordx2 v[106:107], v188, s[34:35] offset:0 sc1
	global_load_dwordx2 v[108:109], v188, s[34:35] offset:512 sc1
	global_load_dwordx2 v[110:111], v188, s[34:35] offset:1024 sc1
	global_load_dwordx2 v[112:113], v188, s[34:35] offset:1536 sc1
	global_load_dwordx4 v[66:69], v194, s[8:9] offset:0 nt
	global_load_dwordx4 v[70:73], v194, s[8:9] offset:1024 nt
	global_load_dwordx4 v[74:77], v194, s[8:9] offset:2048 nt
	global_load_dwordx4 v[78:81], v194, s[8:9] offset:3072 nt
	s_waitcnt vmcnt(24)
	v_lshlrev_b32_e32 v118, 16, v82
	v_and_b32_e32 v119, 0xffff0000, v82
	v_lshlrev_b32_e32 v120, 16, v83
	v_and_b32_e32 v121, 0xffff0000, v83
	v_add_f32_e32 v18, v18, v118
	v_add_f32_e32 v19, v19, v119
	v_add_f32_e32 v20, v20, v120
	v_add_f32_e32 v21, v21, v121
	v_lshlrev_b32_e32 v118, 16, v84
	v_and_b32_e32 v119, 0xffff0000, v84
	v_lshlrev_b32_e32 v120, 16, v85
	v_and_b32_e32 v121, 0xffff0000, v85
	v_add_f32_e32 v22, v22, v118
	v_add_f32_e32 v23, v23, v119
	v_add_f32_e32 v24, v24, v120
	v_add_f32_e32 v25, v25, v121
	v_lshlrev_b32_e32 v118, 16, v86
	v_and_b32_e32 v119, 0xffff0000, v86
	v_lshlrev_b32_e32 v120, 16, v87
	v_and_b32_e32 v121, 0xffff0000, v87
	v_add_f32_e32 v26, v26, v118
	v_add_f32_e32 v27, v27, v119
	v_add_f32_e32 v28, v28, v120
	v_add_f32_e32 v29, v29, v121
	v_lshlrev_b32_e32 v118, 16, v88
	v_and_b32_e32 v119, 0xffff0000, v88
	v_lshlrev_b32_e32 v120, 16, v89
	v_and_b32_e32 v121, 0xffff0000, v89
	v_add_f32_e32 v30, v30, v118
	v_add_f32_e32 v31, v31, v119
	v_add_f32_e32 v32, v32, v120
	v_add_f32_e32 v33, v33, v121
	v_mul_f32_e32 v114, v18, v18
	v_fmac_f32_e32 v114, v19, v19
	v_fmac_f32_e32 v114, v20, v20
	v_fmac_f32_e32 v114, v21, v21
	v_fmac_f32_e32 v114, v22, v22
	v_fmac_f32_e32 v114, v23, v23
	v_fmac_f32_e32 v114, v24, v24
	v_fmac_f32_e32 v114, v25, v25
	v_fmac_f32_e32 v114, v26, v26
	v_fmac_f32_e32 v114, v27, v27
	v_fmac_f32_e32 v114, v28, v28
	v_fmac_f32_e32 v114, v29, v29
	v_fmac_f32_e32 v114, v30, v30
	v_fmac_f32_e32 v114, v31, v31
	v_fmac_f32_e32 v114, v32, v32
	v_fmac_f32_e32 v114, v33, v33
	ds_bpermute_b32 v115, v142, v114
	s_waitcnt lgkmcnt(0)
	v_add_f32_e32 v114, v114, v115
	ds_bpermute_b32 v115, v143, v114
	s_waitcnt lgkmcnt(0)
	v_add_f32_e32 v114, v114, v115
	ds_bpermute_b32 v115, v144, v114
	s_waitcnt lgkmcnt(0)
	v_add_f32_e32 v114, v114, v115
	ds_bpermute_b32 v115, v145, v114
	s_waitcnt lgkmcnt(0)
	v_add_f32_e32 v114, v114, v115
	ds_bpermute_b32 v115, v146, v114
	s_waitcnt lgkmcnt(0)
	v_add_f32_e32 v114, v114, v115
	ds_bpermute_b32 v115, v147, v114
	s_waitcnt lgkmcnt(0)
	v_add_f32_e32 v114, v114, v115
	v_fmamk_f32 v114, v114, 0x3a800000, v124
	v_rsq_f32_e32 v116, v114
	s_nop 0
	v_mul_f32_e32 v118, v116, v196
	v_mul_f32_e32 v18, v18, v118
	v_mul_f32_e32 v119, v116, v197
	v_mul_f32_e32 v19, v19, v119
	v_mul_f32_e32 v120, v116, v198
	v_mul_f32_e32 v20, v20, v120
	v_mul_f32_e32 v121, v116, v199
	v_mul_f32_e32 v21, v21, v121
	global_store_dwordx4 v194, v[18:21], s[44:45] offset:0 nt
	v_mul_f32_e32 v118, v116, v200
	v_mul_f32_e32 v22, v22, v118
	v_mul_f32_e32 v119, v116, v201
	v_mul_f32_e32 v23, v23, v119
	v_mul_f32_e32 v120, v116, v202
	v_mul_f32_e32 v24, v24, v120
	v_mul_f32_e32 v121, v116, v203
	v_mul_f32_e32 v25, v25, v121
	global_store_dwordx4 v194, v[22:25], s[44:45] offset:1024 nt
	v_mul_f32_e32 v118, v116, v204
	v_mul_f32_e32 v26, v26, v118
	v_mul_f32_e32 v119, v116, v205
	v_mul_f32_e32 v27, v27, v119
	v_mul_f32_e32 v120, v116, v206
	v_mul_f32_e32 v28, v28, v120
	v_mul_f32_e32 v121, v116, v207
	v_mul_f32_e32 v29, v29, v121
	global_store_dwordx4 v194, v[26:29], s[44:45] offset:2048 nt
	v_mul_f32_e32 v118, v116, v208
	v_mul_f32_e32 v30, v30, v118
	v_mul_f32_e32 v119, v116, v209
	v_mul_f32_e32 v31, v31, v119
	v_mul_f32_e32 v120, v116, v210
	v_mul_f32_e32 v32, v32, v120
	v_mul_f32_e32 v121, v116, v211
	v_mul_f32_e32 v33, v33, v121
	global_store_dwordx4 v194, v[30:33], s[44:45] offset:3072 nt
	s_add_u32 s2, s52, 0x4000
	s_addc_u32 s3, s53, 0
	s_add_u32 s44, s56, 0x4000
	s_addc_u32 s45, s57, 0
	s_add_u32 s26, s54, 0x2000
	s_addc_u32 s27, s55, 0
	global_load_dwordx2 v[82:83], v188, s[26:27] offset:0 sc1
	global_load_dwordx2 v[84:85], v188, s[26:27] offset:512 sc1
	global_load_dwordx2 v[86:87], v188, s[26:27] offset:1024 sc1
	global_load_dwordx2 v[88:89], v188, s[26:27] offset:1536 sc1
	global_load_dwordx4 v[18:21], v194, s[2:3] offset:0 nt
	global_load_dwordx4 v[22:25], v194, s[2:3] offset:1024 nt
	global_load_dwordx4 v[26:29], v194, s[2:3] offset:2048 nt
	global_load_dwordx4 v[30:33], v194, s[2:3] offset:3072 nt
	s_waitcnt vmcnt(28)
	v_lshlrev_b32_e32 v118, 16, v90
	v_and_b32_e32 v119, 0xffff0000, v90
	v_lshlrev_b32_e32 v120, 16, v91
	v_and_b32_e32 v121, 0xffff0000, v91
	v_add_f32_e32 v34, v34, v118
	v_add_f32_e32 v35, v35, v119
	v_add_f32_e32 v36, v36, v120
	v_add_f32_e32 v37, v37, v121
	v_lshlrev_b32_e32 v118, 16, v92
	v_and_b32_e32 v119, 0xffff0000, v92
	v_lshlrev_b32_e32 v120, 16, v93
	v_and_b32_e32 v121, 0xffff0000, v93
	v_add_f32_e32 v38, v38, v118
	v_add_f32_e32 v39, v39, v119
	v_add_f32_e32 v40, v40, v120
	v_add_f32_e32 v41, v41, v121
	v_lshlrev_b32_e32 v118, 16, v94
	v_and_b32_e32 v119, 0xffff0000, v94
	v_lshlrev_b32_e32 v120, 16, v95
	v_and_b32_e32 v121, 0xffff0000, v95
	v_add_f32_e32 v42, v42, v118
	v_add_f32_e32 v43, v43, v119
	v_add_f32_e32 v44, v44, v120
	v_add_f32_e32 v45, v45, v121
	v_lshlrev_b32_e32 v118, 16, v96
	v_and_b32_e32 v119, 0xffff0000, v96
	v_lshlrev_b32_e32 v120, 16, v97
	v_and_b32_e32 v121, 0xffff0000, v97
	v_add_f32_e32 v46, v46, v118
	v_add_f32_e32 v47, v47, v119
	v_add_f32_e32 v48, v48, v120
	v_add_f32_e32 v49, v49, v121
	v_mul_f32_e32 v114, v34, v34
	v_fmac_f32_e32 v114, v35, v35
	v_fmac_f32_e32 v114, v36, v36
	v_fmac_f32_e32 v114, v37, v37
	v_fmac_f32_e32 v114, v38, v38
	v_fmac_f32_e32 v114, v39, v39
	v_fmac_f32_e32 v114, v40, v40
	v_fmac_f32_e32 v114, v41, v41
	v_fmac_f32_e32 v114, v42, v42
	v_fmac_f32_e32 v114, v43, v43
	v_fmac_f32_e32 v114, v44, v44
	v_fmac_f32_e32 v114, v45, v45
	v_fmac_f32_e32 v114, v46, v46
	v_fmac_f32_e32 v114, v47, v47
	v_fmac_f32_e32 v114, v48, v48
	v_fmac_f32_e32 v114, v49, v49
	ds_bpermute_b32 v115, v142, v114
	s_waitcnt lgkmcnt(0)
	v_add_f32_e32 v114, v114, v115
	ds_bpermute_b32 v115, v143, v114
	s_waitcnt lgkmcnt(0)
	v_add_f32_e32 v114, v114, v115
	ds_bpermute_b32 v115, v144, v114
	s_waitcnt lgkmcnt(0)
	v_add_f32_e32 v114, v114, v115
	ds_bpermute_b32 v115, v145, v114
	s_waitcnt lgkmcnt(0)
	v_add_f32_e32 v114, v114, v115
	ds_bpermute_b32 v115, v146, v114
	s_waitcnt lgkmcnt(0)
	v_add_f32_e32 v114, v114, v115
	ds_bpermute_b32 v115, v147, v114
	s_waitcnt lgkmcnt(0)
	v_add_f32_e32 v114, v114, v115
	v_fmamk_f32 v114, v114, 0x3a800000, v124
	v_rsq_f32_e32 v116, v114
	s_nop 0
	v_mul_f32_e32 v118, v116, v196
	v_mul_f32_e32 v34, v34, v118
	v_mul_f32_e32 v119, v116, v197
	v_mul_f32_e32 v35, v35, v119
	v_mul_f32_e32 v120, v116, v198
	v_mul_f32_e32 v36, v36, v120
	v_mul_f32_e32 v121, v116, v199
	v_mul_f32_e32 v37, v37, v121
	global_store_dwordx4 v194, v[34:37], s[46:47] offset:0 nt
	v_mul_f32_e32 v118, v116, v200
	v_mul_f32_e32 v38, v38, v118
	v_mul_f32_e32 v119, v116, v201
	v_mul_f32_e32 v39, v39, v119
	v_mul_f32_e32 v120, v116, v202
	v_mul_f32_e32 v40, v40, v120
	v_mul_f32_e32 v121, v116, v203
	v_mul_f32_e32 v41, v41, v121
	global_store_dwordx4 v194, v[38:41], s[46:47] offset:1024 nt
	v_mul_f32_e32 v118, v116, v204
	v_mul_f32_e32 v42, v42, v118
	v_mul_f32_e32 v119, v116, v205
	v_mul_f32_e32 v43, v43, v119
	v_mul_f32_e32 v120, v116, v206
	v_mul_f32_e32 v44, v44, v120
	v_mul_f32_e32 v121, v116, v207
	v_mul_f32_e32 v45, v45, v121
	global_store_dwordx4 v194, v[42:45], s[46:47] offset:2048 nt
	v_mul_f32_e32 v118, v116, v208
	v_mul_f32_e32 v46, v46, v118
	v_mul_f32_e32 v119, v116, v209
	v_mul_f32_e32 v47, v47, v119
	v_mul_f32_e32 v120, v116, v210
	v_mul_f32_e32 v48, v48, v120
	v_mul_f32_e32 v121, v116, v211
	v_mul_f32_e32 v49, v49, v121
	global_store_dwordx4 v194, v[46:49], s[46:47] offset:3072 nt
	s_add_u32 s4, s52, 0x5000
	s_addc_u32 s5, s53, 0
	s_add_u32 s46, s56, 0x5000
	s_addc_u32 s47, s57, 0
	s_add_u32 s28, s54, 0x2800
	s_addc_u32 s29, s55, 0
	global_load_dwordx2 v[90:91], v188, s[28:29] offset:0 sc1
	global_load_dwordx2 v[92:93], v188, s[28:29] offset:512 sc1
	global_load_dwordx2 v[94:95], v188, s[28:29] offset:1024 sc1
	global_load_dwordx2 v[96:97], v188, s[28:29] offset:1536 sc1
	global_load_dwordx4 v[34:37], v194, s[4:5] offset:0 nt
	global_load_dwordx4 v[38:41], v194, s[4:5] offset:1024 nt
	global_load_dwordx4 v[42:45], v194, s[4:5] offset:2048 nt
	global_load_dwordx4 v[46:49], v194, s[4:5] offset:3072 nt
	s_waitcnt vmcnt(32)
	v_lshlrev_b32_e32 v118, 16, v98
	v_and_b32_e32 v119, 0xffff0000, v98
	v_lshlrev_b32_e32 v120, 16, v99
	v_and_b32_e32 v121, 0xffff0000, v99
	v_add_f32_e32 v50, v50, v118
	v_add_f32_e32 v51, v51, v119
	v_add_f32_e32 v52, v52, v120
	v_add_f32_e32 v53, v53, v121
	v_lshlrev_b32_e32 v118, 16, v100
	v_and_b32_e32 v119, 0xffff0000, v100
	v_lshlrev_b32_e32 v120, 16, v101
	v_and_b32_e32 v121, 0xffff0000, v101
	v_add_f32_e32 v54, v54, v118
	v_add_f32_e32 v55, v55, v119
	v_add_f32_e32 v56, v56, v120
	v_add_f32_e32 v57, v57, v121
	v_lshlrev_b32_e32 v118, 16, v102
	v_and_b32_e32 v119, 0xffff0000, v102
	v_lshlrev_b32_e32 v120, 16, v103
	v_and_b32_e32 v121, 0xffff0000, v103
	v_add_f32_e32 v58, v58, v118
	v_add_f32_e32 v59, v59, v119
	v_add_f32_e32 v60, v60, v120
	v_add_f32_e32 v61, v61, v121
	v_lshlrev_b32_e32 v118, 16, v104
	v_and_b32_e32 v119, 0xffff0000, v104
	v_lshlrev_b32_e32 v120, 16, v105
	v_and_b32_e32 v121, 0xffff0000, v105
	v_add_f32_e32 v62, v62, v118
	v_add_f32_e32 v63, v63, v119
	v_add_f32_e32 v64, v64, v120
	v_add_f32_e32 v65, v65, v121
	v_mul_f32_e32 v114, v50, v50
	v_fmac_f32_e32 v114, v51, v51
	v_fmac_f32_e32 v114, v52, v52
	v_fmac_f32_e32 v114, v53, v53
	v_fmac_f32_e32 v114, v54, v54
	v_fmac_f32_e32 v114, v55, v55
	v_fmac_f32_e32 v114, v56, v56
	v_fmac_f32_e32 v114, v57, v57
	v_fmac_f32_e32 v114, v58, v58
	v_fmac_f32_e32 v114, v59, v59
	v_fmac_f32_e32 v114, v60, v60
	v_fmac_f32_e32 v114, v61, v61
	v_fmac_f32_e32 v114, v62, v62
	v_fmac_f32_e32 v114, v63, v63
	v_fmac_f32_e32 v114, v64, v64
	v_fmac_f32_e32 v114, v65, v65
	ds_bpermute_b32 v115, v142, v114
	s_waitcnt lgkmcnt(0)
	v_add_f32_e32 v114, v114, v115
	ds_bpermute_b32 v115, v143, v114
	s_waitcnt lgkmcnt(0)
	v_add_f32_e32 v114, v114, v115
	ds_bpermute_b32 v115, v144, v114
	s_waitcnt lgkmcnt(0)
	v_add_f32_e32 v114, v114, v115
	ds_bpermute_b32 v115, v145, v114
	s_waitcnt lgkmcnt(0)
	v_add_f32_e32 v114, v114, v115
	ds_bpermute_b32 v115, v146, v114
	s_waitcnt lgkmcnt(0)
	v_add_f32_e32 v114, v114, v115
	ds_bpermute_b32 v115, v147, v114
	s_waitcnt lgkmcnt(0)
	v_add_f32_e32 v114, v114, v115
	v_fmamk_f32 v114, v114, 0x3a800000, v124
	v_rsq_f32_e32 v116, v114
	s_nop 0
	v_mul_f32_e32 v118, v116, v196
	v_mul_f32_e32 v50, v50, v118
	v_mul_f32_e32 v119, v116, v197
	v_mul_f32_e32 v51, v51, v119
	v_mul_f32_e32 v120, v116, v198
	v_mul_f32_e32 v52, v52, v120
	v_mul_f32_e32 v121, v116, v199
	v_mul_f32_e32 v53, v53, v121
	global_store_dwordx4 v194, v[50:53], s[48:49] offset:0 nt
	v_mul_f32_e32 v118, v116, v200
	v_mul_f32_e32 v54, v54, v118
	v_mul_f32_e32 v119, v116, v201
	v_mul_f32_e32 v55, v55, v119
	v_mul_f32_e32 v120, v116, v202
	v_mul_f32_e32 v56, v56, v120
	v_mul_f32_e32 v121, v116, v203
	v_mul_f32_e32 v57, v57, v121
	global_store_dwordx4 v194, v[54:57], s[48:49] offset:1024 nt
	v_mul_f32_e32 v118, v116, v204
	v_mul_f32_e32 v58, v58, v118
	v_mul_f32_e32 v119, v116, v205
	v_mul_f32_e32 v59, v59, v119
	v_mul_f32_e32 v120, v116, v206
	v_mul_f32_e32 v60, v60, v120
	v_mul_f32_e32 v121, v116, v207
	v_mul_f32_e32 v61, v61, v121
	global_store_dwordx4 v194, v[58:61], s[48:49] offset:2048 nt
	v_mul_f32_e32 v118, v116, v208
	v_mul_f32_e32 v62, v62, v118
	v_mul_f32_e32 v119, v116, v209
	v_mul_f32_e32 v63, v63, v119
	v_mul_f32_e32 v120, v116, v210
	v_mul_f32_e32 v64, v64, v120
	v_mul_f32_e32 v121, v116, v211
	v_mul_f32_e32 v65, v65, v121
	global_store_dwordx4 v194, v[62:65], s[48:49] offset:3072 nt
	s_add_u32 s6, s52, 0x6000
	s_addc_u32 s7, s53, 0
	s_add_u32 s48, s56, 0x6000
	s_addc_u32 s49, s57, 0
	s_add_u32 s30, s54, 0x3000
	s_addc_u32 s31, s55, 0
	global_load_dwordx2 v[98:99], v188, s[30:31] offset:0 sc1
	global_load_dwordx2 v[100:101], v188, s[30:31] offset:512 sc1
	global_load_dwordx2 v[102:103], v188, s[30:31] offset:1024 sc1
	global_load_dwordx2 v[104:105], v188, s[30:31] offset:1536 sc1
	global_load_dwordx4 v[50:53], v194, s[6:7] offset:0 nt
	global_load_dwordx4 v[54:57], v194, s[6:7] offset:1024 nt
	global_load_dwordx4 v[58:61], v194, s[6:7] offset:2048 nt
	global_load_dwordx4 v[62:65], v194, s[6:7] offset:3072 nt
	s_waitcnt vmcnt(36)
	v_lshlrev_b32_e32 v118, 16, v106
	v_and_b32_e32 v119, 0xffff0000, v106
	v_lshlrev_b32_e32 v120, 16, v107
	v_and_b32_e32 v121, 0xffff0000, v107
	v_add_f32_e32 v66, v66, v118
	v_add_f32_e32 v67, v67, v119
	v_add_f32_e32 v68, v68, v120
	v_add_f32_e32 v69, v69, v121
	v_lshlrev_b32_e32 v118, 16, v108
	v_and_b32_e32 v119, 0xffff0000, v108
	v_lshlrev_b32_e32 v120, 16, v109
	v_and_b32_e32 v121, 0xffff0000, v109
	v_add_f32_e32 v70, v70, v118
	v_add_f32_e32 v71, v71, v119
	v_add_f32_e32 v72, v72, v120
	v_add_f32_e32 v73, v73, v121
	v_lshlrev_b32_e32 v118, 16, v110
	v_and_b32_e32 v119, 0xffff0000, v110
	v_lshlrev_b32_e32 v120, 16, v111
	v_and_b32_e32 v121, 0xffff0000, v111
	v_add_f32_e32 v74, v74, v118
	v_add_f32_e32 v75, v75, v119
	v_add_f32_e32 v76, v76, v120
	v_add_f32_e32 v77, v77, v121
	v_lshlrev_b32_e32 v118, 16, v112
	v_and_b32_e32 v119, 0xffff0000, v112
	v_lshlrev_b32_e32 v120, 16, v113
	v_and_b32_e32 v121, 0xffff0000, v113
	v_add_f32_e32 v78, v78, v118
	v_add_f32_e32 v79, v79, v119
	v_add_f32_e32 v80, v80, v120
	v_add_f32_e32 v81, v81, v121
	v_mul_f32_e32 v114, v66, v66
	v_fmac_f32_e32 v114, v67, v67
	v_fmac_f32_e32 v114, v68, v68
	v_fmac_f32_e32 v114, v69, v69
	v_fmac_f32_e32 v114, v70, v70
	v_fmac_f32_e32 v114, v71, v71
	v_fmac_f32_e32 v114, v72, v72
	v_fmac_f32_e32 v114, v73, v73
	v_fmac_f32_e32 v114, v74, v74
	v_fmac_f32_e32 v114, v75, v75
	v_fmac_f32_e32 v114, v76, v76
	v_fmac_f32_e32 v114, v77, v77
	v_fmac_f32_e32 v114, v78, v78
	v_fmac_f32_e32 v114, v79, v79
	v_fmac_f32_e32 v114, v80, v80
	v_fmac_f32_e32 v114, v81, v81
	ds_bpermute_b32 v115, v142, v114
	s_waitcnt lgkmcnt(0)
	v_add_f32_e32 v114, v114, v115
	ds_bpermute_b32 v115, v143, v114
	s_waitcnt lgkmcnt(0)
	v_add_f32_e32 v114, v114, v115
	ds_bpermute_b32 v115, v144, v114
	s_waitcnt lgkmcnt(0)
	v_add_f32_e32 v114, v114, v115
	ds_bpermute_b32 v115, v145, v114
	s_waitcnt lgkmcnt(0)
	v_add_f32_e32 v114, v114, v115
	ds_bpermute_b32 v115, v146, v114
	s_waitcnt lgkmcnt(0)
	v_add_f32_e32 v114, v114, v115
	ds_bpermute_b32 v115, v147, v114
	s_waitcnt lgkmcnt(0)
	v_add_f32_e32 v114, v114, v115
	v_fmamk_f32 v114, v114, 0x3a800000, v124
	v_rsq_f32_e32 v116, v114
	s_nop 0
	v_mul_f32_e32 v118, v116, v196
	v_mul_f32_e32 v66, v66, v118
	v_mul_f32_e32 v119, v116, v197
	v_mul_f32_e32 v67, v67, v119
	v_mul_f32_e32 v120, v116, v198
	v_mul_f32_e32 v68, v68, v120
	v_mul_f32_e32 v121, v116, v199
	v_mul_f32_e32 v69, v69, v121
	global_store_dwordx4 v194, v[66:69], s[50:51] offset:0 nt
	v_mul_f32_e32 v118, v116, v200
	v_mul_f32_e32 v70, v70, v118
	v_mul_f32_e32 v119, v116, v201
	v_mul_f32_e32 v71, v71, v119
	v_mul_f32_e32 v120, v116, v202
	v_mul_f32_e32 v72, v72, v120
	v_mul_f32_e32 v121, v116, v203
	v_mul_f32_e32 v73, v73, v121
	global_store_dwordx4 v194, v[70:73], s[50:51] offset:1024 nt
	v_mul_f32_e32 v118, v116, v204
	v_mul_f32_e32 v74, v74, v118
	v_mul_f32_e32 v119, v116, v205
	v_mul_f32_e32 v75, v75, v119
	v_mul_f32_e32 v120, v116, v206
	v_mul_f32_e32 v76, v76, v120
	v_mul_f32_e32 v121, v116, v207
	v_mul_f32_e32 v77, v77, v121
	global_store_dwordx4 v194, v[74:77], s[50:51] offset:2048 nt
	v_mul_f32_e32 v118, v116, v208
	v_mul_f32_e32 v78, v78, v118
	v_mul_f32_e32 v119, v116, v209
	v_mul_f32_e32 v79, v79, v119
	v_mul_f32_e32 v120, v116, v210
	v_mul_f32_e32 v80, v80, v120
	v_mul_f32_e32 v121, v116, v211
	v_mul_f32_e32 v81, v81, v121
	global_store_dwordx4 v194, v[78:81], s[50:51] offset:3072 nt
	s_add_u32 s8, s52, 0x7000
	s_addc_u32 s9, s53, 0
	s_add_u32 s50, s56, 0x7000
	s_addc_u32 s51, s57, 0
	s_add_u32 s34, s54, 0x3800
	s_addc_u32 s35, s55, 0
	global_load_dwordx2 v[106:107], v188, s[34:35] offset:0 sc1
	global_load_dwordx2 v[108:109], v188, s[34:35] offset:512 sc1
	global_load_dwordx2 v[110:111], v188, s[34:35] offset:1024 sc1
	global_load_dwordx2 v[112:113], v188, s[34:35] offset:1536 sc1
	global_load_dwordx4 v[66:69], v194, s[8:9] offset:0 nt
	global_load_dwordx4 v[70:73], v194, s[8:9] offset:1024 nt
	global_load_dwordx4 v[74:77], v194, s[8:9] offset:2048 nt
	global_load_dwordx4 v[78:81], v194, s[8:9] offset:3072 nt
	s_waitcnt vmcnt(36)
	v_lshlrev_b32_e32 v118, 16, v82
	v_and_b32_e32 v119, 0xffff0000, v82
	v_lshlrev_b32_e32 v120, 16, v83
	v_and_b32_e32 v121, 0xffff0000, v83
	v_add_f32_e32 v18, v18, v118
	v_add_f32_e32 v19, v19, v119
	v_add_f32_e32 v20, v20, v120
	v_add_f32_e32 v21, v21, v121
	v_lshlrev_b32_e32 v118, 16, v84
	v_and_b32_e32 v119, 0xffff0000, v84
	v_lshlrev_b32_e32 v120, 16, v85
	v_and_b32_e32 v121, 0xffff0000, v85
	v_add_f32_e32 v22, v22, v118
	v_add_f32_e32 v23, v23, v119
	v_add_f32_e32 v24, v24, v120
	v_add_f32_e32 v25, v25, v121
	v_lshlrev_b32_e32 v118, 16, v86
	v_and_b32_e32 v119, 0xffff0000, v86
	v_lshlrev_b32_e32 v120, 16, v87
	v_and_b32_e32 v121, 0xffff0000, v87
	v_add_f32_e32 v26, v26, v118
	v_add_f32_e32 v27, v27, v119
	v_add_f32_e32 v28, v28, v120
	v_add_f32_e32 v29, v29, v121
	v_lshlrev_b32_e32 v118, 16, v88
	v_and_b32_e32 v119, 0xffff0000, v88
	v_lshlrev_b32_e32 v120, 16, v89
	v_and_b32_e32 v121, 0xffff0000, v89
	v_add_f32_e32 v30, v30, v118
	v_add_f32_e32 v31, v31, v119
	v_add_f32_e32 v32, v32, v120
	v_add_f32_e32 v33, v33, v121
	v_mul_f32_e32 v114, v18, v18
	v_fmac_f32_e32 v114, v19, v19
	v_fmac_f32_e32 v114, v20, v20
	v_fmac_f32_e32 v114, v21, v21
	v_fmac_f32_e32 v114, v22, v22
	v_fmac_f32_e32 v114, v23, v23
	v_fmac_f32_e32 v114, v24, v24
	v_fmac_f32_e32 v114, v25, v25
	v_fmac_f32_e32 v114, v26, v26
	v_fmac_f32_e32 v114, v27, v27
	v_fmac_f32_e32 v114, v28, v28
	v_fmac_f32_e32 v114, v29, v29
	v_fmac_f32_e32 v114, v30, v30
	v_fmac_f32_e32 v114, v31, v31
	v_fmac_f32_e32 v114, v32, v32
	v_fmac_f32_e32 v114, v33, v33
	ds_bpermute_b32 v115, v142, v114
	s_waitcnt lgkmcnt(0)
	v_add_f32_e32 v114, v114, v115
	ds_bpermute_b32 v115, v143, v114
	s_waitcnt lgkmcnt(0)
	v_add_f32_e32 v114, v114, v115
	ds_bpermute_b32 v115, v144, v114
	s_waitcnt lgkmcnt(0)
	v_add_f32_e32 v114, v114, v115
	ds_bpermute_b32 v115, v145, v114
	s_waitcnt lgkmcnt(0)
	v_add_f32_e32 v114, v114, v115
	ds_bpermute_b32 v115, v146, v114
	s_waitcnt lgkmcnt(0)
	v_add_f32_e32 v114, v114, v115
	ds_bpermute_b32 v115, v147, v114
	s_waitcnt lgkmcnt(0)
	v_add_f32_e32 v114, v114, v115
	v_fmamk_f32 v114, v114, 0x3a800000, v124
	v_rsq_f32_e32 v116, v114
	s_nop 0
	v_mul_f32_e32 v118, v116, v196
	v_mul_f32_e32 v18, v18, v118
	v_mul_f32_e32 v119, v116, v197
	v_mul_f32_e32 v19, v19, v119
	v_mul_f32_e32 v120, v116, v198
	v_mul_f32_e32 v20, v20, v120
	v_mul_f32_e32 v121, v116, v199
	v_mul_f32_e32 v21, v21, v121
	global_store_dwordx4 v194, v[18:21], s[44:45] offset:0 nt
	v_mul_f32_e32 v118, v116, v200
	v_mul_f32_e32 v22, v22, v118
	v_mul_f32_e32 v119, v116, v201
	v_mul_f32_e32 v23, v23, v119
	v_mul_f32_e32 v120, v116, v202
	v_mul_f32_e32 v24, v24, v120
	v_mul_f32_e32 v121, v116, v203
	v_mul_f32_e32 v25, v25, v121
	global_store_dwordx4 v194, v[22:25], s[44:45] offset:1024 nt
	v_mul_f32_e32 v118, v116, v204
	v_mul_f32_e32 v26, v26, v118
	v_mul_f32_e32 v119, v116, v205
	v_mul_f32_e32 v27, v27, v119
	v_mul_f32_e32 v120, v116, v206
	v_mul_f32_e32 v28, v28, v120
	v_mul_f32_e32 v121, v116, v207
	v_mul_f32_e32 v29, v29, v121
	global_store_dwordx4 v194, v[26:29], s[44:45] offset:2048 nt
	v_mul_f32_e32 v118, v116, v208
	v_mul_f32_e32 v30, v30, v118
	v_mul_f32_e32 v119, v116, v209
	v_mul_f32_e32 v31, v31, v119
	v_mul_f32_e32 v120, v116, v210
	v_mul_f32_e32 v32, v32, v120
	v_mul_f32_e32 v121, v116, v211
	v_mul_f32_e32 v33, v33, v121
	global_store_dwordx4 v194, v[30:33], s[44:45] offset:3072 nt
	s_waitcnt vmcnt(28)
	v_lshlrev_b32_e32 v118, 16, v90
	v_and_b32_e32 v119, 0xffff0000, v90
	v_lshlrev_b32_e32 v120, 16, v91
	v_and_b32_e32 v121, 0xffff0000, v91
	v_add_f32_e32 v34, v34, v118
	v_add_f32_e32 v35, v35, v119
	v_add_f32_e32 v36, v36, v120
	v_add_f32_e32 v37, v37, v121
	v_lshlrev_b32_e32 v118, 16, v92
	v_and_b32_e32 v119, 0xffff0000, v92
	v_lshlrev_b32_e32 v120, 16, v93
	v_and_b32_e32 v121, 0xffff0000, v93
	v_add_f32_e32 v38, v38, v118
	v_add_f32_e32 v39, v39, v119
	v_add_f32_e32 v40, v40, v120
	v_add_f32_e32 v41, v41, v121
	v_lshlrev_b32_e32 v118, 16, v94
	v_and_b32_e32 v119, 0xffff0000, v94
	v_lshlrev_b32_e32 v120, 16, v95
	v_and_b32_e32 v121, 0xffff0000, v95
	v_add_f32_e32 v42, v42, v118
	v_add_f32_e32 v43, v43, v119
	v_add_f32_e32 v44, v44, v120
	v_add_f32_e32 v45, v45, v121
	v_lshlrev_b32_e32 v118, 16, v96
	v_and_b32_e32 v119, 0xffff0000, v96
	v_lshlrev_b32_e32 v120, 16, v97
	v_and_b32_e32 v121, 0xffff0000, v97
	v_add_f32_e32 v46, v46, v118
	v_add_f32_e32 v47, v47, v119
	v_add_f32_e32 v48, v48, v120
	v_add_f32_e32 v49, v49, v121
	v_mul_f32_e32 v114, v34, v34
	v_fmac_f32_e32 v114, v35, v35
	v_fmac_f32_e32 v114, v36, v36
	v_fmac_f32_e32 v114, v37, v37
	v_fmac_f32_e32 v114, v38, v38
	v_fmac_f32_e32 v114, v39, v39
	v_fmac_f32_e32 v114, v40, v40
	v_fmac_f32_e32 v114, v41, v41
	v_fmac_f32_e32 v114, v42, v42
	v_fmac_f32_e32 v114, v43, v43
	v_fmac_f32_e32 v114, v44, v44
	v_fmac_f32_e32 v114, v45, v45
	v_fmac_f32_e32 v114, v46, v46
	v_fmac_f32_e32 v114, v47, v47
	v_fmac_f32_e32 v114, v48, v48
	v_fmac_f32_e32 v114, v49, v49
	ds_bpermute_b32 v115, v142, v114
	s_waitcnt lgkmcnt(0)
	v_add_f32_e32 v114, v114, v115
	ds_bpermute_b32 v115, v143, v114
	s_waitcnt lgkmcnt(0)
	v_add_f32_e32 v114, v114, v115
	ds_bpermute_b32 v115, v144, v114
	s_waitcnt lgkmcnt(0)
	v_add_f32_e32 v114, v114, v115
	ds_bpermute_b32 v115, v145, v114
	s_waitcnt lgkmcnt(0)
	v_add_f32_e32 v114, v114, v115
	ds_bpermute_b32 v115, v146, v114
	s_waitcnt lgkmcnt(0)
	v_add_f32_e32 v114, v114, v115
	ds_bpermute_b32 v115, v147, v114
	s_waitcnt lgkmcnt(0)
	v_add_f32_e32 v114, v114, v115
	v_fmamk_f32 v114, v114, 0x3a800000, v124
	v_rsq_f32_e32 v116, v114
	s_nop 0
	v_mul_f32_e32 v118, v116, v196
	v_mul_f32_e32 v34, v34, v118
	v_mul_f32_e32 v119, v116, v197
	v_mul_f32_e32 v35, v35, v119
	v_mul_f32_e32 v120, v116, v198
	v_mul_f32_e32 v36, v36, v120
	v_mul_f32_e32 v121, v116, v199
	v_mul_f32_e32 v37, v37, v121
	global_store_dwordx4 v194, v[34:37], s[46:47] offset:0 nt
	v_mul_f32_e32 v118, v116, v200
	v_mul_f32_e32 v38, v38, v118
	v_mul_f32_e32 v119, v116, v201
	v_mul_f32_e32 v39, v39, v119
	v_mul_f32_e32 v120, v116, v202
	v_mul_f32_e32 v40, v40, v120
	v_mul_f32_e32 v121, v116, v203
	v_mul_f32_e32 v41, v41, v121
	global_store_dwordx4 v194, v[38:41], s[46:47] offset:1024 nt
	v_mul_f32_e32 v118, v116, v204
	v_mul_f32_e32 v42, v42, v118
	v_mul_f32_e32 v119, v116, v205
	v_mul_f32_e32 v43, v43, v119
	v_mul_f32_e32 v120, v116, v206
	v_mul_f32_e32 v44, v44, v120
	v_mul_f32_e32 v121, v116, v207
	v_mul_f32_e32 v45, v45, v121
	global_store_dwordx4 v194, v[42:45], s[46:47] offset:2048 nt
	v_mul_f32_e32 v118, v116, v208
	v_mul_f32_e32 v46, v46, v118
	v_mul_f32_e32 v119, v116, v209
	v_mul_f32_e32 v47, v47, v119
	v_mul_f32_e32 v120, v116, v210
	v_mul_f32_e32 v48, v48, v120
	v_mul_f32_e32 v121, v116, v211
	v_mul_f32_e32 v49, v49, v121
	global_store_dwordx4 v194, v[46:49], s[46:47] offset:3072 nt
	s_waitcnt vmcnt(20)
	v_lshlrev_b32_e32 v118, 16, v98
	v_and_b32_e32 v119, 0xffff0000, v98
	v_lshlrev_b32_e32 v120, 16, v99
	v_and_b32_e32 v121, 0xffff0000, v99
	v_add_f32_e32 v50, v50, v118
	v_add_f32_e32 v51, v51, v119
	v_add_f32_e32 v52, v52, v120
	v_add_f32_e32 v53, v53, v121
	v_lshlrev_b32_e32 v118, 16, v100
	v_and_b32_e32 v119, 0xffff0000, v100
	v_lshlrev_b32_e32 v120, 16, v101
	v_and_b32_e32 v121, 0xffff0000, v101
	v_add_f32_e32 v54, v54, v118
	v_add_f32_e32 v55, v55, v119
	v_add_f32_e32 v56, v56, v120
	v_add_f32_e32 v57, v57, v121
	v_lshlrev_b32_e32 v118, 16, v102
	v_and_b32_e32 v119, 0xffff0000, v102
	v_lshlrev_b32_e32 v120, 16, v103
	v_and_b32_e32 v121, 0xffff0000, v103
	v_add_f32_e32 v58, v58, v118
	v_add_f32_e32 v59, v59, v119
	v_add_f32_e32 v60, v60, v120
	v_add_f32_e32 v61, v61, v121
	v_lshlrev_b32_e32 v118, 16, v104
	v_and_b32_e32 v119, 0xffff0000, v104
	v_lshlrev_b32_e32 v120, 16, v105
	v_and_b32_e32 v121, 0xffff0000, v105
	v_add_f32_e32 v62, v62, v118
	v_add_f32_e32 v63, v63, v119
	v_add_f32_e32 v64, v64, v120
	v_add_f32_e32 v65, v65, v121
	v_mul_f32_e32 v114, v50, v50
	v_fmac_f32_e32 v114, v51, v51
	v_fmac_f32_e32 v114, v52, v52
	v_fmac_f32_e32 v114, v53, v53
	v_fmac_f32_e32 v114, v54, v54
	v_fmac_f32_e32 v114, v55, v55
	v_fmac_f32_e32 v114, v56, v56
	v_fmac_f32_e32 v114, v57, v57
	v_fmac_f32_e32 v114, v58, v58
	v_fmac_f32_e32 v114, v59, v59
	v_fmac_f32_e32 v114, v60, v60
	v_fmac_f32_e32 v114, v61, v61
	v_fmac_f32_e32 v114, v62, v62
	v_fmac_f32_e32 v114, v63, v63
	v_fmac_f32_e32 v114, v64, v64
	v_fmac_f32_e32 v114, v65, v65
	ds_bpermute_b32 v115, v142, v114
	s_waitcnt lgkmcnt(0)
	v_add_f32_e32 v114, v114, v115
	ds_bpermute_b32 v115, v143, v114
	s_waitcnt lgkmcnt(0)
	v_add_f32_e32 v114, v114, v115
	ds_bpermute_b32 v115, v144, v114
	s_waitcnt lgkmcnt(0)
	v_add_f32_e32 v114, v114, v115
	ds_bpermute_b32 v115, v145, v114
	s_waitcnt lgkmcnt(0)
	v_add_f32_e32 v114, v114, v115
	ds_bpermute_b32 v115, v146, v114
	s_waitcnt lgkmcnt(0)
	v_add_f32_e32 v114, v114, v115
	ds_bpermute_b32 v115, v147, v114
	s_waitcnt lgkmcnt(0)
	v_add_f32_e32 v114, v114, v115
	v_fmamk_f32 v114, v114, 0x3a800000, v124
	v_rsq_f32_e32 v116, v114
	s_nop 0
	v_mul_f32_e32 v118, v116, v196
	v_mul_f32_e32 v50, v50, v118
	v_mul_f32_e32 v119, v116, v197
	v_mul_f32_e32 v51, v51, v119
	v_mul_f32_e32 v120, v116, v198
	v_mul_f32_e32 v52, v52, v120
	v_mul_f32_e32 v121, v116, v199
	v_mul_f32_e32 v53, v53, v121
	global_store_dwordx4 v194, v[50:53], s[48:49] offset:0 nt
	v_mul_f32_e32 v118, v116, v200
	v_mul_f32_e32 v54, v54, v118
	v_mul_f32_e32 v119, v116, v201
	v_mul_f32_e32 v55, v55, v119
	v_mul_f32_e32 v120, v116, v202
	v_mul_f32_e32 v56, v56, v120
	v_mul_f32_e32 v121, v116, v203
	v_mul_f32_e32 v57, v57, v121
	global_store_dwordx4 v194, v[54:57], s[48:49] offset:1024 nt
	v_mul_f32_e32 v118, v116, v204
	v_mul_f32_e32 v58, v58, v118
	v_mul_f32_e32 v119, v116, v205
	v_mul_f32_e32 v59, v59, v119
	v_mul_f32_e32 v120, v116, v206
	v_mul_f32_e32 v60, v60, v120
	v_mul_f32_e32 v121, v116, v207
	v_mul_f32_e32 v61, v61, v121
	global_store_dwordx4 v194, v[58:61], s[48:49] offset:2048 nt
	v_mul_f32_e32 v118, v116, v208
	v_mul_f32_e32 v62, v62, v118
	v_mul_f32_e32 v119, v116, v209
	v_mul_f32_e32 v63, v63, v119
	v_mul_f32_e32 v120, v116, v210
	v_mul_f32_e32 v64, v64, v120
	v_mul_f32_e32 v121, v116, v211
	v_mul_f32_e32 v65, v65, v121
	global_store_dwordx4 v194, v[62:65], s[48:49] offset:3072 nt
	s_waitcnt vmcnt(12)
	v_lshlrev_b32_e32 v118, 16, v106
	v_and_b32_e32 v119, 0xffff0000, v106
	v_lshlrev_b32_e32 v120, 16, v107
	v_and_b32_e32 v121, 0xffff0000, v107
	v_add_f32_e32 v66, v66, v118
	v_add_f32_e32 v67, v67, v119
	v_add_f32_e32 v68, v68, v120
	v_add_f32_e32 v69, v69, v121
	v_lshlrev_b32_e32 v118, 16, v108
	v_and_b32_e32 v119, 0xffff0000, v108
	v_lshlrev_b32_e32 v120, 16, v109
	v_and_b32_e32 v121, 0xffff0000, v109
	v_add_f32_e32 v70, v70, v118
	v_add_f32_e32 v71, v71, v119
	v_add_f32_e32 v72, v72, v120
	v_add_f32_e32 v73, v73, v121
	v_lshlrev_b32_e32 v118, 16, v110
	v_and_b32_e32 v119, 0xffff0000, v110
	v_lshlrev_b32_e32 v120, 16, v111
	v_and_b32_e32 v121, 0xffff0000, v111
	v_add_f32_e32 v74, v74, v118
	v_add_f32_e32 v75, v75, v119
	v_add_f32_e32 v76, v76, v120
	v_add_f32_e32 v77, v77, v121
	v_lshlrev_b32_e32 v118, 16, v112
	v_and_b32_e32 v119, 0xffff0000, v112
	v_lshlrev_b32_e32 v120, 16, v113
	v_and_b32_e32 v121, 0xffff0000, v113
	v_add_f32_e32 v78, v78, v118
	v_add_f32_e32 v79, v79, v119
	v_add_f32_e32 v80, v80, v120
	v_add_f32_e32 v81, v81, v121
	v_mul_f32_e32 v114, v66, v66
	v_fmac_f32_e32 v114, v67, v67
	v_fmac_f32_e32 v114, v68, v68
	v_fmac_f32_e32 v114, v69, v69
	v_fmac_f32_e32 v114, v70, v70
	v_fmac_f32_e32 v114, v71, v71
	v_fmac_f32_e32 v114, v72, v72
	v_fmac_f32_e32 v114, v73, v73
	v_fmac_f32_e32 v114, v74, v74
	v_fmac_f32_e32 v114, v75, v75
	v_fmac_f32_e32 v114, v76, v76
	v_fmac_f32_e32 v114, v77, v77
	v_fmac_f32_e32 v114, v78, v78
	v_fmac_f32_e32 v114, v79, v79
	v_fmac_f32_e32 v114, v80, v80
	v_fmac_f32_e32 v114, v81, v81
	ds_bpermute_b32 v115, v142, v114
	s_waitcnt lgkmcnt(0)
	v_add_f32_e32 v114, v114, v115
	ds_bpermute_b32 v115, v143, v114
	s_waitcnt lgkmcnt(0)
	v_add_f32_e32 v114, v114, v115
	ds_bpermute_b32 v115, v144, v114
	s_waitcnt lgkmcnt(0)
	v_add_f32_e32 v114, v114, v115
	ds_bpermute_b32 v115, v145, v114
	s_waitcnt lgkmcnt(0)
	v_add_f32_e32 v114, v114, v115
	ds_bpermute_b32 v115, v146, v114
	s_waitcnt lgkmcnt(0)
	v_add_f32_e32 v114, v114, v115
	ds_bpermute_b32 v115, v147, v114
	s_waitcnt lgkmcnt(0)
	v_add_f32_e32 v114, v114, v115
	v_fmamk_f32 v114, v114, 0x3a800000, v124
	v_rsq_f32_e32 v116, v114
	s_nop 0
	v_mul_f32_e32 v118, v116, v196
	v_mul_f32_e32 v66, v66, v118
	v_mul_f32_e32 v119, v116, v197
	v_mul_f32_e32 v67, v67, v119
	v_mul_f32_e32 v120, v116, v198
	v_mul_f32_e32 v68, v68, v120
	v_mul_f32_e32 v121, v116, v199
	v_mul_f32_e32 v69, v69, v121
	global_store_dwordx4 v194, v[66:69], s[50:51] offset:0 nt
	v_mul_f32_e32 v118, v116, v200
	v_mul_f32_e32 v70, v70, v118
	v_mul_f32_e32 v119, v116, v201
	v_mul_f32_e32 v71, v71, v119
	v_mul_f32_e32 v120, v116, v202
	v_mul_f32_e32 v72, v72, v120
	v_mul_f32_e32 v121, v116, v203
	v_mul_f32_e32 v73, v73, v121
	global_store_dwordx4 v194, v[70:73], s[50:51] offset:1024 nt
	v_mul_f32_e32 v118, v116, v204
	v_mul_f32_e32 v74, v74, v118
	v_mul_f32_e32 v119, v116, v205
	v_mul_f32_e32 v75, v75, v119
	v_mul_f32_e32 v120, v116, v206
	v_mul_f32_e32 v76, v76, v120
	v_mul_f32_e32 v121, v116, v207
	v_mul_f32_e32 v77, v77, v121
	global_store_dwordx4 v194, v[74:77], s[50:51] offset:2048 nt
	v_mul_f32_e32 v118, v116, v208
	v_mul_f32_e32 v78, v78, v118
	v_mul_f32_e32 v119, v116, v209
	v_mul_f32_e32 v79, v79, v119
	v_mul_f32_e32 v120, v116, v210
	v_mul_f32_e32 v80, v80, v120
	v_mul_f32_e32 v121, v116, v211
	v_mul_f32_e32 v81, v81, v121
	global_store_dwordx4 v194, v[78:81], s[50:51] offset:3072 nt
	s_add_i32 s83, s83, 1
	s_branch .Lp45_loop
